# MoBA: key blocks visited in ascending order (step s -> block s>>1) so the 32 workgroups of an XCD share each K/V^T block in L2; on top of the bank-conflict-free tiles
# baseline (speedup 1.0000x reference)
.LBB0_97:
	s_or_b64 exec, exec, s[0:1]
	s_waitcnt lgkmcnt(0)
	s_barrier
	ds_read2st64_b32 v[36:37], v164 offset1:1
	ds_read_b32 v139, v159
	s_and_b32 s34, s8, -2
	s_lshl_b32 s52, s47, 8
	s_add_i32 s48, s34, 2
	s_waitcnt lgkmcnt(1)
	v_or_b32_e32 v36, v37, v36
	ds_bpermute_b32 v37, v169, v36
	s_waitcnt lgkmcnt(1)
	ds_bpermute_b32 v53, v160, v139
	s_mov_b64 s[10:11], 0
	s_mov_b32 s51, 0
	s_cmp_lt_i32 s8, 0
	s_waitcnt lgkmcnt(1)
	v_or_b32_e32 v44, v36, v37
	ds_bpermute_b32 v45, v168, v44
	s_waitcnt lgkmcnt(1)
	v_or_b32_e32 v53, v53, v139
	ds_bpermute_b32 v56, v161, v53
	ds_read_b128 v[36:39], v192
	ds_read_b128 v[40:43], v192 offset:64
	s_mov_b64 s[24:25], 0
	s_waitcnt lgkmcnt(3)
	v_or_b32_e32 v54, v44, v45
	ds_bpermute_b32 v55, v163, v54
	s_waitcnt lgkmcnt(3)
	v_or_b32_e32 v53, v53, v56
	ds_bpermute_b32 v56, v162, v53
	ds_read_b128 v[44:47], v192 offset:128
	ds_read_b128 v[48:51], v192 offset:192
	s_waitcnt lgkmcnt(3)
	v_or_b32_e32 v54, v54, v55
	ds_bpermute_b32 v55, v162, v54
	s_waitcnt lgkmcnt(3)
	v_or_b32_e32 v53, v53, v56
	ds_bpermute_b32 v56, v163, v53
	s_waitcnt lgkmcnt(1)
	v_or_b32_e32 v54, v54, v55
	ds_bpermute_b32 v55, v161, v54
	s_waitcnt lgkmcnt(1)
	v_or_b32_e32 v53, v53, v56
	s_waitcnt lgkmcnt(0)
	v_or_b32_e32 v54, v54, v55
	ds_bpermute_b32 v55, v160, v54
	v_readfirstlane_b32 s49, v53
	s_waitcnt lgkmcnt(0)
	v_or_b32_e32 v53, v54, v55
	s_nop 0
	v_readfirstlane_b32 s50, v53
	s_or_b32 s9, s46, 0x7f
	s_add_i32 s82, s48, -2
	s_mov_b32 s51, 0
.Lms_s51:
	s_cmp_ge_i32 s51, s48
	s_cbranch_scc1 .Lms_a_done
	s_lshr_b32 s0, s51, 1
	s_lshr_b32 s0, s50, s0
	s_bitcmp1_b32 s0, 0
	s_cbranch_scc0 .Lms_s51_next
	s_lshl_b32 s0, s51, 7
	s_cmp_le_i32 s0, s9
	s_cbranch_scc1 .Lms_a_done
.Lms_s51_next:
	s_add_i32 s51, s51, 1
	s_branch .Lms_s51
.Lms_a_done:
	s_cmp_lt_i32 s51, s48
	s_cselect_b64 s[24:25], -1, 0
	s_add_i32 s14, s51, 1
.Lms_s14:
	s_cmp_ge_i32 s14, s48
	s_cbranch_scc1 .Lms_b_done
	s_lshr_b32 s0, s14, 1
	s_lshr_b32 s0, s50, s0
	s_bitcmp1_b32 s0, 0
	s_cbranch_scc0 .Lms_s14_next
	s_lshl_b32 s0, s14, 7
	s_cmp_le_i32 s0, s9
	s_cbranch_scc1 .Lms_b_done
.Lms_s14_next:
	s_add_i32 s14, s14, 1
	s_branch .Lms_s14
.Lms_b_done:
	s_min_i32 s14, s14, s48
	s_cmp_lt_i32 s14, s48
	s_cselect_b64 s[10:11], -1, 0
.LBB0_130:
	v_cndmask_b32_e64 v53, 0, 1, s[24:25]
	v_cmp_ne_u32_e64 s[0:1], 1, v53
	s_andn2_b64 vcc, exec, s[24:25]
	s_cbranch_vccnz .LBB0_132
	s_lshr_b32 s8, s51, 1
	s_nop 0
	s_lshl_b32 s9, s51, 7
	s_lshl_b32 s8, s8, 8
	s_and_b32 s9, s9, 0x80
	s_or_b32 s8, s8, s9
	s_ashr_i32 s9, s8, 31
	v_lshl_add_u64 v[4:5], v[140:141], 0, s[8:9]
	v_mov_b64_e32 v[6:7], s[88:89]
	v_lshl_add_u64 v[28:29], s[8:9], 1, v[118:119]
	v_mad_u64_u32 v[6:7], s[8:9], v4, s72, v[6:7]
	v_mad_i32_i24 v7, v5, s72, v7
	v_lshl_add_u64 v[4:5], v[6:7], 0, s[20:21]
	v_lshl_add_u64 v[30:31], v[4:5], 0, v[2:3]
	v_add_co_u32_e32 v4, vcc, s3, v30
	s_mov_b32 s8, 0x3d000
	s_nop 0
	v_addc_co_u32_e32 v5, vcc, 0, v31, vcc
	v_add_co_u32_e32 v12, vcc, s8, v30
	v_lshl_add_u64 v[8:9], v[28:29], 0, v[146:147]
	s_nop 0
	v_addc_co_u32_e32 v13, vcc, 0, v31, vcc
	v_add_co_u32_e32 v20, vcc, 0x79000, v30
	v_lshl_add_u64 v[16:17], v[28:29], 0, v[148:149]
	s_nop 0
	v_addc_co_u32_e32 v21, vcc, 0, v31, vcc
	v_add_co_u32_e32 v30, vcc, 0xb5000, v30
	v_lshl_add_u64 v[24:25], v[28:29], 0, v[150:151]
	s_nop 0
	v_addc_co_u32_e32 v31, vcc, 0, v31, vcc
	v_lshl_add_u64 v[32:33], v[28:29], 0, v[152:153]
	global_load_dwordx4 v[4:7], v[4:5], off offset:1024
	s_nop 0
	global_load_dwordx4 v[8:11], v[8:9], off
	s_nop 0
	global_load_dwordx4 v[12:15], v[12:13], off offset:1024
	s_nop 0
	global_load_dwordx4 v[16:19], v[16:17], off
	s_nop 0
	global_load_dwordx4 v[20:23], v[20:21], off offset:1024
	s_nop 0
	global_load_dwordx4 v[24:27], v[24:25], off
	s_nop 0
	global_load_dwordx4 v[28:31], v[30:31], off offset:1024
	s_nop 0
	global_load_dwordx4 v[32:35], v[32:33], off
.LBB0_132:
	s_waitcnt lgkmcnt(0)
	s_barrier
	s_and_b64 vcc, exec, s[0:1]
	s_cbranch_vccnz .LBB0_135
	v_add_u32_e32 v53, 0x8800, v193
	s_waitcnt vmcnt(7)
	ds_write_b128 v217, v[4:7]
	s_waitcnt vmcnt(6)
	ds_write2_b64 v53, v[8:9], v[10:11] offset1:2
	s_waitcnt vmcnt(5)
	ds_write_b128 v217, v[12:15] offset:8704
	v_add_u32_e32 v53, 0xa800, v193
	s_waitcnt vmcnt(4)
	ds_write2_b64 v53, v[16:17], v[18:19] offset0:64 offset1:66
	s_waitcnt vmcnt(3)
	ds_write_b128 v217, v[20:23] offset:17408
	v_add_u32_e32 v53, 0xc800, v193
	s_waitcnt vmcnt(2)
	ds_write2_b64 v53, v[24:25], v[26:27] offset0:128 offset1:130
	s_waitcnt vmcnt(1)
	ds_write_b128 v217, v[28:31] offset:26112
	v_add_u32_e32 v52, 0xe800, v193
	s_andn2_b64 vcc, exec, s[10:11]
	s_waitcnt vmcnt(0)
	ds_write2_b64 v52, v[32:33], v[34:35] offset0:192 offset1:194
	s_cbranch_vccnz .LBB0_135
	s_lshr_b32 s0, s14, 1
	s_nop 0
	s_lshl_b32 s1, s14, 7
	s_lshl_b32 s0, s0, 8
	s_and_b32 s1, s1, 0x80
	s_or_b32 s0, s0, s1
	s_ashr_i32 s1, s0, 31
	v_lshl_add_u64 v[4:5], v[140:141], 0, s[0:1]
	v_mov_b64_e32 v[6:7], s[88:89]
	v_lshl_add_u64 v[28:29], s[0:1], 1, v[118:119]
	v_mad_u64_u32 v[6:7], s[0:1], v4, s72, v[6:7]
	v_mad_i32_i24 v7, v5, s72, v7
	v_lshl_add_u64 v[4:5], v[6:7], 0, s[20:21]
	v_lshl_add_u64 v[30:31], v[4:5], 0, v[2:3]
	v_add_co_u32_e32 v4, vcc, s3, v30
	s_mov_b32 s0, 0x3d000
	s_nop 0
	v_addc_co_u32_e32 v5, vcc, 0, v31, vcc
	v_add_co_u32_e32 v12, vcc, s0, v30
	v_lshl_add_u64 v[8:9], v[28:29], 0, v[146:147]
	s_nop 0
	v_addc_co_u32_e32 v13, vcc, 0, v31, vcc
	v_add_co_u32_e32 v20, vcc, 0x79000, v30
	v_lshl_add_u64 v[16:17], v[28:29], 0, v[148:149]
	s_nop 0
	v_addc_co_u32_e32 v21, vcc, 0, v31, vcc
	v_add_co_u32_e32 v30, vcc, 0xb5000, v30
	v_lshl_add_u64 v[24:25], v[28:29], 0, v[150:151]
	s_nop 0
	v_addc_co_u32_e32 v31, vcc, 0, v31, vcc
	v_lshl_add_u64 v[32:33], v[28:29], 0, v[152:153]
	global_load_dwordx4 v[4:7], v[4:5], off offset:1024
	s_nop 0
	global_load_dwordx4 v[8:11], v[8:9], off
	s_nop 0
	global_load_dwordx4 v[12:15], v[12:13], off offset:1024
	s_nop 0
	global_load_dwordx4 v[16:19], v[16:17], off
	s_nop 0
	global_load_dwordx4 v[20:23], v[20:21], off offset:1024
	s_nop 0
	global_load_dwordx4 v[24:27], v[24:25], off
	s_nop 0
	global_load_dwordx4 v[28:31], v[30:31], off offset:1024
	s_nop 0
	global_load_dwordx4 v[32:35], v[32:33], off
.LBB0_135:
	s_cmp_ge_i32 s51, s48
	v_add_u32_e32 v154, s46, v157
	s_cbranch_scc1 .LBB0_91
	v_mov_b32_e32 v54, v3
	v_mov_b32_e32 v55, v3
	v_mov_b32_e32 v52, v3
	v_mov_b32_e32 v53, v3
	v_mov_b64_e32 v[58:59], v[54:55]
	v_mov_b64_e32 v[62:63], v[54:55]
	v_mov_b64_e32 v[66:67], v[54:55]
	v_mov_b64_e32 v[70:71], v[54:55]
	v_mov_b64_e32 v[74:75], v[54:55]
	v_mov_b64_e32 v[78:79], v[54:55]
	v_mov_b64_e32 v[82:83], v[54:55]
	s_or_b32 s12, s46, 0x7f
	v_mov_b32_e32 v155, v120
	s_movk_i32 s13, 0x80
	s_mov_b32 s15, 0
	v_mov_b32_e32 v194, 0
	v_mov_b32_e32 v196, 0xff800000
	v_mov_b64_e32 v[56:57], v[52:53]
	v_mov_b64_e32 v[60:61], v[52:53]
	v_mov_b64_e32 v[64:65], v[52:53]
	v_mov_b64_e32 v[68:69], v[52:53]
	v_mov_b64_e32 v[72:73], v[52:53]
	v_mov_b64_e32 v[76:77], v[52:53]
	v_mov_b64_e32 v[80:81], v[52:53]
	s_branch .LBB0_139

.LBB0_142:
	s_ashr_i32 s0, s10, 1
	s_nop 0
	s_lshr_b32 s0, s50, s0
	s_bitcmp0_b32 s0, 0
	s_mov_b64 s[0:1], -1
	s_mov_b64 s[8:9], -1
	s_cbranch_scc1 .LBB0_145
	s_cmp_gt_i32 s11, s12
	s_cselect_b64 s[8:9], -1, 0

.LBB0_148:
	s_cmp_ge_i32 s16, s48
	s_cselect_b64 s[8:9], -1, 0
	s_and_b64 vcc, exec, s[8:9]
	s_cbranch_vccnz .LBB0_151
	s_xor_b32 s10, s15, 1
	s_mul_i32 s10, s10, 0x11000
	s_add_i32 s10, s10, 0
	v_add3_u32 v85, s10, v165, v216
	v_add3_u32 v84, s10, v0, v216
	v_add_u32_e32 v86, 0x8800, v85
	s_waitcnt vmcnt(7)
	ds_write_b128 v84, v[4:7]
	s_waitcnt vmcnt(6)
	ds_write2_b64 v86, v[8:9], v[10:11] offset1:2
	s_waitcnt vmcnt(5)
	ds_write_b128 v84, v[12:15] offset:8704
	v_add_u32_e32 v86, 0xa800, v85
	s_waitcnt vmcnt(4)
	ds_write2_b64 v86, v[16:17], v[18:19] offset0:64 offset1:66
	s_waitcnt vmcnt(3)
	ds_write_b128 v84, v[20:23] offset:17408
	v_add_u32_e32 v86, 0xc800, v85
	s_waitcnt vmcnt(2)
	ds_write2_b64 v86, v[24:25], v[26:27] offset0:128 offset1:130
	s_waitcnt vmcnt(1)
	ds_write_b128 v84, v[28:31] offset:26112
	v_add_u32_e32 v84, 0xe800, v85
	s_andn2_b64 vcc, exec, s[0:1]
	s_waitcnt vmcnt(0)
	ds_write2_b64 v84, v[32:33], v[34:35] offset0:192 offset1:194
	s_cbranch_vccnz .LBB0_151
	s_lshr_b32 s0, s14, 1
	s_nop 0
	s_lshl_b32 s1, s14, 7
	s_lshl_b32 s0, s0, 8
	s_and_b32 s1, s1, 0x80
	s_or_b32 s0, s0, s1
	s_ashr_i32 s1, s0, 31
	v_lshl_add_u64 v[4:5], v[140:141], 0, s[0:1]
	v_mov_b64_e32 v[6:7], s[88:89]
	v_lshl_add_u64 v[28:29], s[0:1], 1, v[118:119]
	v_mad_u64_u32 v[6:7], s[0:1], v4, s72, v[6:7]
	v_mad_i32_i24 v7, v5, s72, v7
	v_lshl_add_u64 v[4:5], v[6:7], 0, s[20:21]
	v_lshl_add_u64 v[30:31], v[4:5], 0, v[2:3]
	v_add_co_u32_e32 v4, vcc, s3, v30
	s_mov_b32 s0, 0x3d000
	s_nop 0
	v_addc_co_u32_e32 v5, vcc, 0, v31, vcc
	v_add_co_u32_e32 v12, vcc, s0, v30
	v_lshl_add_u64 v[8:9], v[28:29], 0, v[146:147]
	s_nop 0
	v_addc_co_u32_e32 v13, vcc, 0, v31, vcc
	v_add_co_u32_e32 v20, vcc, 0x79000, v30
	v_lshl_add_u64 v[16:17], v[28:29], 0, v[148:149]
	s_nop 0
	v_addc_co_u32_e32 v21, vcc, 0, v31, vcc
	v_add_co_u32_e32 v30, vcc, 0xb5000, v30
	v_lshl_add_u64 v[24:25], v[28:29], 0, v[150:151]
	s_nop 0
	v_addc_co_u32_e32 v31, vcc, 0, v31, vcc
	v_lshl_add_u64 v[32:33], v[28:29], 0, v[152:153]
	global_load_dwordx4 v[4:7], v[4:5], off offset:1024
	s_nop 0
	global_load_dwordx4 v[8:11], v[8:9], off
	s_nop 0
	global_load_dwordx4 v[12:15], v[12:13], off offset:1024
	s_nop 0
	global_load_dwordx4 v[16:19], v[16:17], off
	s_nop 0
	global_load_dwordx4 v[20:23], v[20:21], off offset:1024
	s_nop 0
	global_load_dwordx4 v[24:27], v[24:25], off
	s_nop 0
	global_load_dwordx4 v[28:31], v[30:31], off offset:1024
	s_nop 0
	global_load_dwordx4 v[32:35], v[32:33], off
.LBB0_151:
	s_ashr_i32 s0, s51, 1
	s_nop 0
	s_lshl_b32 s0, 1, s0
	s_and_b32 s1, s0, s49
	s_cmp_eq_u32 s1, 0
	s_cbranch_scc1 .LBB0_137
	s_mul_i32 s1, s15, 0x11000
	s_add_i32 s1, s1, 0
	v_add_u32_e32 v84, s1, v167
	v_add_u32_e32 v195, v84, v158
	v_add3_u32 v197, s1, v158, v167
	ds_read_b128 v[84:87], v195
	ds_read_b128 v[88:91], v195 offset:64
	ds_read_b128 v[92:95], v195 offset:128
	ds_read_b128 v[96:99], v195 offset:192
	ds_read_b128 v[100:103], v197 offset:272
	ds_read_b128 v[104:107], v197 offset:336
	ds_read_b128 v[108:111], v197 offset:400
	ds_read_b128 v[198:201], v197 offset:464
	s_waitcnt lgkmcnt(4)
	v_mfma_f32_16x16x32_bf16 v[84:87], v[84:87], v[36:39], 0
	v_mfma_f32_16x16x32_bf16 v[84:87], v[88:91], v[40:43], v[84:87]
	v_mfma_f32_16x16x32_bf16 v[84:87], v[92:95], v[44:47], v[84:87]
	v_mfma_f32_16x16x32_bf16 v[112:115], v[96:99], v[48:51], v[84:87]
	s_nop 5
	ds_read_b128 v[84:87], v197 offset:8704
	ds_read_b128 v[88:91], v197 offset:8768
	ds_read_b128 v[92:95], v197 offset:8832
	ds_read_b128 v[96:99], v197 offset:8896
	s_waitcnt lgkmcnt(4)
	v_mfma_f32_16x16x32_bf16 v[100:103], v[100:103], v[36:39], 0
	v_mfma_f32_16x16x32_bf16 v[100:103], v[104:107], v[40:43], v[100:103]
	v_mfma_f32_16x16x32_bf16 v[100:103], v[108:111], v[44:47], v[100:103]
	v_mfma_f32_16x16x32_bf16 v[108:111], v[198:201], v[48:51], v[100:103]
	s_nop 5
	ds_read_b128 v[100:103], v197 offset:8976
	ds_read_b128 v[198:201], v197 offset:9040
	ds_read_b128 v[202:205], v197 offset:9104
	ds_read_b128 v[206:209], v197 offset:9168
	s_waitcnt lgkmcnt(4)
	v_mfma_f32_16x16x32_bf16 v[84:87], v[84:87], v[36:39], 0
	v_mfma_f32_16x16x32_bf16 v[84:87], v[88:91], v[40:43], v[84:87]
	v_mfma_f32_16x16x32_bf16 v[84:87], v[92:95], v[44:47], v[84:87]
	v_mfma_f32_16x16x32_bf16 v[104:107], v[96:99], v[48:51], v[84:87]
	s_nop 5
	ds_read_b128 v[84:87], v197 offset:17408
	ds_read_b128 v[88:91], v197 offset:17472
	ds_read_b128 v[92:95], v197 offset:17536
	ds_read_b128 v[96:99], v197 offset:17600
	s_waitcnt lgkmcnt(4)
	v_mfma_f32_16x16x32_bf16 v[100:103], v[100:103], v[36:39], 0
	v_mfma_f32_16x16x32_bf16 v[100:103], v[198:201], v[40:43], v[100:103]
	v_mfma_f32_16x16x32_bf16 v[100:103], v[202:205], v[44:47], v[100:103]
	v_mfma_f32_16x16x32_bf16 v[100:103], v[206:209], v[48:51], v[100:103]
	ds_read_b128 v[198:201], v197 offset:17680
	ds_read_b128 v[202:205], v197 offset:17744
	ds_read_b128 v[206:209], v197 offset:17808
	ds_read_b128 v[230:233], v197 offset:17872
	s_waitcnt lgkmcnt(4)
	v_mfma_f32_16x16x32_bf16 v[84:87], v[84:87], v[36:39], 0
	v_mfma_f32_16x16x32_bf16 v[84:87], v[88:91], v[40:43], v[84:87]
	v_mfma_f32_16x16x32_bf16 v[84:87], v[92:95], v[44:47], v[84:87]
	v_mfma_f32_16x16x32_bf16 v[96:99], v[96:99], v[48:51], v[84:87]
	s_nop 5
	ds_read_b128 v[84:87], v197 offset:26112
	ds_read_b128 v[88:91], v197 offset:26176
	ds_read_b128 v[234:237], v197 offset:26240
	ds_read_b128 v[238:241], v197 offset:26304
	s_waitcnt lgkmcnt(4)
	v_mfma_f32_16x16x32_bf16 v[92:95], v[198:201], v[36:39], 0
	v_mfma_f32_16x16x32_bf16 v[92:95], v[202:205], v[40:43], v[92:95]
	v_mfma_f32_16x16x32_bf16 v[92:95], v[206:209], v[44:47], v[92:95]
	v_mfma_f32_16x16x32_bf16 v[92:95], v[230:233], v[48:51], v[92:95]
	ds_read_b128 v[198:201], v197 offset:26384
	ds_read_b128 v[202:205], v197 offset:26448
	ds_read_b128 v[206:209], v197 offset:26512
	ds_read_b128 v[230:233], v197 offset:26576
	s_waitcnt lgkmcnt(4)
	v_mfma_f32_16x16x32_bf16 v[84:87], v[84:87], v[36:39], 0
	v_mfma_f32_16x16x32_bf16 v[84:87], v[88:91], v[40:43], v[84:87]
	v_mfma_f32_16x16x32_bf16 v[84:87], v[234:237], v[44:47], v[84:87]
	v_mfma_f32_16x16x32_bf16 v[88:91], v[238:241], v[48:51], v[84:87]
	s_waitcnt lgkmcnt(0)
	v_mfma_f32_16x16x32_bf16 v[84:87], v[198:201], v[36:39], 0
	v_mfma_f32_16x16x32_bf16 v[84:87], v[202:205], v[40:43], v[84:87]
	v_mfma_f32_16x16x32_bf16 v[84:87], v[206:209], v[44:47], v[84:87]
	v_mfma_f32_16x16x32_bf16 v[84:87], v[230:233], v[48:51], v[84:87]
	ds_read_b128 v[202:205], v195 offset:34816
	ds_read_b128 v[206:209], v195 offset:35088
	ds_read_b128 v[230:233], v195 offset:43520
	ds_read_b128 v[234:237], v195 offset:43792
	v_and_b32_e32 v197, s0, v139
	v_cmp_eq_u32_e64 s[0:1], 0, v197
	s_cmp_ge_u32 s51, s82
	s_mov_b64 s[10:11], -1
	s_cbranch_scc1 .LBB0_154
	v_max3_f32 v197, v112, v113, v114
	v_max3_f32 v198, v96, v97, v98
	v_max3_f32 v197, v197, v115, v108
	v_max3_f32 v198, v198, v99, v92
	v_max3_f32 v197, v197, v109, v110
	v_max3_f32 v198, v198, v93, v94
	v_max3_f32 v197, v197, v111, v104
	v_max3_f32 v198, v198, v95, v88
	v_max3_f32 v197, v197, v105, v106
	v_max3_f32 v198, v198, v89, v90
	v_max3_f32 v197, v197, v107, v100
	v_max3_f32 v198, v198, v91, v84
	v_max3_f32 v197, v197, v101, v102
	v_max3_f32 v198, v198, v85, v86
	v_max_f32_e32 v197, v197, v103
	v_max_f32_e32 v198, v198, v87
	v_max_f32_e32 v197, v197, v198
	v_cndmask_b32_e64 v197, v197, v215, s[0:1]
	s_mov_b64 s[10:11], 0
